# gemm_sample_rows: first K tile's LDS-DMA issued at item start, before the rstd prologue (bases computed from SGPRs)
# speedup vs baseline: 1.0185x; 1.0023x over previous
; template <int NH>
; __device__ void gemm_sample_rows(const Params& p, const u16* __restrict__ A, const u16* __restrict__ Bt,
;                                  const float* __restrict__ resid, float* __restrict__ outf, unsigned char* smem, const int rep) {
;     ...
;   for (int item0 = blockIdx.x; item0 < 256 * rep; item0 += gridDim.x) {
;     const int item = item0 & 255;
;     const int m0 = NPROMPT + (item >> 4) * 64, n0 = (item & 15) * 64;
;     for (int idx = tid; idx < 64 * NH; idx += NTHR) {
;       const int row = idx / NH, h = idx % NH;
;       const float* pp = parts + (size_t)(m0 + row) * 64 + h * (64 / NH);
;       float sm = 0.f;
; #pragma unroll
;       for (int q = 0; q < 64 / NH; ++q) sm += pp[q];
;       rstdS[idx] = rsqrtf(sm / (float)(K / NH) + 1e-6f);
;     }
;     f32x4 acc[4][4];
; #pragma unroll
;     for (int i = 0; i < 4; ++i)
; #pragma unroll
;       for (int j = 0; j < 4; ++j) acc[i][j] = (f32x4){0.f, 0.f, 0.f, 0.f};
;     const u16* ap = A + (size_t)(m0 + l15) * K + w * 256 + 8 * g;
;     const u16* bp = Bt + (size_t)(n0 + l15) * K + w * 256 + 8 * g;
.Lsrmap3:
.LBB0_726:
	s_lshr_b32 s55, s29, 4
	s_and_b32 s55, s55, 15
	s_lshl_b32 s55, s55, 18
	s_add_u32 s55, s55, 0x15262000
	v_readlane_b32 s54, v255, 6
	s_lshl_b32 s56, s54, 9
	s_add_u32 s55, s55, s56
	s_add_u32 s50, s84, s55
	s_addc_u32 s51, s85, 0
	s_and_b32 s55, s29, 15
	s_lshl_b32 s55, s55, 18
	s_add_u32 s55, s55, 0xc00000
	s_add_u32 s55, s55, s56
	s_add_u32 s52, s84, s55
	s_addc_u32 s53, s85, 0
	s_lshl_b32 s54, s54, 14
	v_mbcnt_lo_u32_b32 v240, -1, 0
	v_mbcnt_hi_u32_b32 v240, -1, v240
	v_lshrrev_b32_e32 v241, 3, v240
	v_lshlrev_b32_e32 v241, 12, v241
	v_and_b32_e32 v242, 7, v240
	v_lshrrev_b32_e32 v243, 4, v240
	v_xor_b32_e32 v244, v242, v243
	v_lshl_add_u32 v232, v244, 4, v241
	v_xor_b32_e32 v244, 4, v244
	v_lshl_add_u32 v233, v244, 4, v241
	v_add_u32_e32 v233, 0x8000, v233
	v_add_u32_e32 v234, 0x10000, v232
	v_add_u32_e32 v235, 0x10000, v233
	v_add_u32_e32 v236, 0x20000, v232
	v_add_u32_e32 v237, 0x20000, v233
	v_add_u32_e32 v238, 0x30000, v232
	v_add_u32_e32 v239, 0x30000, v233
	v_and_b32_e32 v245, 15, v240
	v_lshrrev_b32_e32 v246, 1, v245
	v_xor_b32_e32 v246, v243, v246
	v_lshlrev_b32_e32 v246, 4, v246
	v_lshl_add_u32 v246, v245, 7, v246
	v_add_u32_e32 v246, s54, v246
	v_xor_b32_e32 v247, 64, v246
	s_add_u32 m0, s54, 0x0
	s_nop 0
	global_load_lds_dwordx4 v232, s[50:51]
	s_add_u32 m0, s54, 0x400
	s_nop 0
	global_load_lds_dwordx4 v233, s[50:51]
	s_add_u32 m0, s54, 0x800
	s_nop 0
	global_load_lds_dwordx4 v234, s[50:51]
	s_add_u32 m0, s54, 0xc00
	s_nop 0
	global_load_lds_dwordx4 v235, s[50:51]
	s_add_u32 m0, s54, 0x1000
	s_nop 0
	global_load_lds_dwordx4 v236, s[50:51]
	s_add_u32 m0, s54, 0x1400
	s_nop 0
	global_load_lds_dwordx4 v237, s[50:51]
	s_add_u32 m0, s54, 0x1800
	s_nop 0
	global_load_lds_dwordx4 v238, s[50:51]
	s_add_u32 m0, s54, 0x1c00
	s_nop 0
	global_load_lds_dwordx4 v239, s[50:51]
	s_add_u32 m0, s54, 0x2000
	s_nop 0
	global_load_lds_dwordx4 v232, s[52:53]
	s_add_u32 m0, s54, 0x2400
	s_nop 0
	global_load_lds_dwordx4 v233, s[52:53]
	s_add_u32 m0, s54, 0x2800
	s_nop 0
	global_load_lds_dwordx4 v234, s[52:53]
	s_add_u32 m0, s54, 0x2c00
	s_nop 0
	global_load_lds_dwordx4 v235, s[52:53]
	s_add_u32 m0, s54, 0x3000
	s_nop 0
	global_load_lds_dwordx4 v236, s[52:53]
	s_add_u32 m0, s54, 0x3400
	s_nop 0
	global_load_lds_dwordx4 v237, s[52:53]
	s_add_u32 m0, s54, 0x3800
	s_nop 0
	global_load_lds_dwordx4 v238, s[52:53]
	s_add_u32 m0, s54, 0x3c00
	s_nop 0
	global_load_lds_dwordx4 v239, s[52:53]
	s_add_u32 s50, s50, 0x80
	s_addc_u32 s51, s51, 0
	s_add_u32 s52, s52, 0x80
	s_addc_u32 s53, s53, 0
	s_lshl_b32 s0, s29, 2
	s_and_b32 s0, s0, 0x3c0
	s_or_b32 s30, s0, 0x4000
	s_and_saveexec_b64 s[4:5], vcc
	s_cbranch_execz .LBB0_729
	s_mov_b64 s[8:9], 0
	v_mov_b32_e32 v0, v122
	v_mov_b32_e32 v1, v198
	v_mov_b32_e32 v2, v196

; template <int NH>
; __device__ void gemm_sample_rows(const Params& p, const u16* __restrict__ A, const u16* __restrict__ Bt,
;                                  const float* __restrict__ resid, float* __restrict__ outf, unsigned char* smem, const int rep) {
;     ...
;     const u16* ap = A + (size_t)(m0 + l15) * K + w * 256 + 8 * g;
;     const u16* bp = Bt + (size_t)(n0 + l15) * K + w * 256 + 8 * g;
; #pragma unroll 2
;     for (int ks = 0; ks < 8; ++ks) {
;       bf16x8 af[4], bfr[4];
; #pragma unroll
;       for (int mf = 0; mf < 4; ++mf) af[mf] = *(const bf16x8*)(ap + (size_t)(mf * 16) * K + ks * 32);
; #pragma unroll
;       for (int nf = 0; nf < 4; ++nf) bfr[nf] = *(const bf16x8*)(bp + (size_t)(nf * 16) * K + ks * 32);
; #pragma unroll
;       for (int mf = 0; mf < 4; ++mf)
; #pragma unroll
;         for (int nf = 0; nf < 4; ++nf)
;           acc[mf][nf] = __builtin_amdgcn_mfma_f32_16x16x32_bf16(af[mf], bfr[nf], acc[mf][nf], 0, 0, 0);
;     }
.LBB0_730:
	s_waitcnt vmcnt(0)
	ds_read_b128 v[124:127], v246
	ds_read_b128 v[128:131], v246 offset:2048
	ds_read_b128 v[132:135], v246 offset:4096
	ds_read_b128 v[136:139], v246 offset:6144
	ds_read_b128 v[200:203], v246 offset:8192
	ds_read_b128 v[204:207], v246 offset:10240
	ds_read_b128 v[208:211], v246 offset:12288
	ds_read_b128 v[212:215], v246 offset:14336
	ds_read_b128 v[140:143], v247
	ds_read_b128 v[144:147], v247 offset:2048
	ds_read_b128 v[148:151], v247 offset:4096
	ds_read_b128 v[152:155], v247 offset:6144
	ds_read_b128 v[216:219], v247 offset:8192
	ds_read_b128 v[220:223], v247 offset:10240
	ds_read_b128 v[224:227], v247 offset:12288
	ds_read_b128 v[228:231], v247 offset:14336
	s_waitcnt lgkmcnt(0)
	s_add_u32 m0, s54, 0x0
	s_nop 0
	global_load_lds_dwordx4 v232, s[50:51]
	s_add_u32 m0, s54, 0x400
	s_nop 0
	global_load_lds_dwordx4 v233, s[50:51]
	s_add_u32 m0, s54, 0x800
	s_nop 0
	global_load_lds_dwordx4 v234, s[50:51]
	s_add_u32 m0, s54, 0xc00
	s_nop 0
	global_load_lds_dwordx4 v235, s[50:51]
	s_add_u32 m0, s54, 0x1000
	s_nop 0
	global_load_lds_dwordx4 v236, s[50:51]
	s_add_u32 m0, s54, 0x1400
	s_nop 0
	global_load_lds_dwordx4 v237, s[50:51]
	s_add_u32 m0, s54, 0x1800
	s_nop 0
	global_load_lds_dwordx4 v238, s[50:51]
	s_add_u32 m0, s54, 0x1c00
	s_nop 0
	global_load_lds_dwordx4 v239, s[50:51]
	s_add_u32 m0, s54, 0x2000
	s_nop 0
	global_load_lds_dwordx4 v232, s[52:53]
	s_add_u32 m0, s54, 0x2400
	s_nop 0
	global_load_lds_dwordx4 v233, s[52:53]
	s_add_u32 m0, s54, 0x2800
	s_nop 0
	global_load_lds_dwordx4 v234, s[52:53]
	s_add_u32 m0, s54, 0x2c00
	s_nop 0
	global_load_lds_dwordx4 v235, s[52:53]
	s_add_u32 m0, s54, 0x3000
	s_nop 0
	global_load_lds_dwordx4 v236, s[52:53]
	s_add_u32 m0, s54, 0x3400
	s_nop 0
	global_load_lds_dwordx4 v237, s[52:53]
	s_add_u32 m0, s54, 0x3800
	s_nop 0
	global_load_lds_dwordx4 v238, s[52:53]
	s_add_u32 m0, s54, 0x3c00
	s_nop 0
	global_load_lds_dwordx4 v239, s[52:53]
	s_add_u32 s50, s50, 0x80
	s_addc_u32 s51, s51, 0
	s_add_u32 s52, s52, 0x80
	s_addc_u32 s53, s53, 0
	v_mfma_f32_16x16x32_bf16 v[60:63], v[124:127], v[200:203], v[60:63]
	v_mfma_f32_16x16x32_bf16 v[52:55], v[124:127], v[204:207], v[52:55]
	v_mfma_f32_16x16x32_bf16 v[48:51], v[124:127], v[208:211], v[48:51]
	v_mfma_f32_16x16x32_bf16 v[44:47], v[124:127], v[212:215], v[44:47]
	v_mfma_f32_16x16x32_bf16 v[40:43], v[128:131], v[200:203], v[40:43]
	v_mfma_f32_16x16x32_bf16 v[36:39], v[128:131], v[204:207], v[36:39]
	v_mfma_f32_16x16x32_bf16 v[20:23], v[128:131], v[208:211], v[20:23]
	v_mfma_f32_16x16x32_bf16 v[12:15], v[128:131], v[212:215], v[12:15]
	v_mfma_f32_16x16x32_bf16 v[16:19], v[132:135], v[200:203], v[16:19]
	v_mfma_f32_16x16x32_bf16 v[24:27], v[132:135], v[204:207], v[24:27]
	v_mfma_f32_16x16x32_bf16 v[28:31], v[132:135], v[208:211], v[28:31]
	v_mfma_f32_16x16x32_bf16 v[32:35], v[132:135], v[212:215], v[32:35]
	v_mfma_f32_16x16x32_bf16 v[0:3], v[136:139], v[200:203], v[0:3]
	v_mfma_f32_16x16x32_bf16 v[4:7], v[136:139], v[204:207], v[4:7]
	v_mfma_f32_16x16x32_bf16 v[8:11], v[136:139], v[208:211], v[8:11]
	v_mfma_f32_16x16x32_bf16 v[56:59], v[136:139], v[212:215], v[56:59]
	v_mfma_f32_16x16x32_bf16 v[60:63], v[140:143], v[216:219], v[60:63]
	v_mfma_f32_16x16x32_bf16 v[52:55], v[140:143], v[220:223], v[52:55]
	v_mfma_f32_16x16x32_bf16 v[48:51], v[140:143], v[224:227], v[48:51]
	v_mfma_f32_16x16x32_bf16 v[44:47], v[140:143], v[228:231], v[44:47]
	v_mfma_f32_16x16x32_bf16 v[40:43], v[144:147], v[216:219], v[40:43]
	v_mfma_f32_16x16x32_bf16 v[36:39], v[144:147], v[220:223], v[36:39]
	v_mfma_f32_16x16x32_bf16 v[20:23], v[144:147], v[224:227], v[20:23]
	v_mfma_f32_16x16x32_bf16 v[12:15], v[144:147], v[228:231], v[12:15]
	v_mfma_f32_16x16x32_bf16 v[16:19], v[148:151], v[216:219], v[16:19]
	v_mfma_f32_16x16x32_bf16 v[24:27], v[148:151], v[220:223], v[24:27]
	v_mfma_f32_16x16x32_bf16 v[28:31], v[148:151], v[224:227], v[28:31]
	v_mfma_f32_16x16x32_bf16 v[32:35], v[148:151], v[228:231], v[32:35]
	v_mfma_f32_16x16x32_bf16 v[0:3], v[152:155], v[216:219], v[0:3]
	v_mfma_f32_16x16x32_bf16 v[4:7], v[152:155], v[220:223], v[4:7]
	v_mfma_f32_16x16x32_bf16 v[8:11], v[152:155], v[224:227], v[8:11]
	v_mfma_f32_16x16x32_bf16 v[56:59], v[152:155], v[228:231], v[56:59]
	s_waitcnt vmcnt(0)
	ds_read_b128 v[124:127], v246
	ds_read_b128 v[128:131], v246 offset:2048
	ds_read_b128 v[132:135], v246 offset:4096
	ds_read_b128 v[136:139], v246 offset:6144
	ds_read_b128 v[200:203], v246 offset:8192
	ds_read_b128 v[204:207], v246 offset:10240
	ds_read_b128 v[208:211], v246 offset:12288
	ds_read_b128 v[212:215], v246 offset:14336
	ds_read_b128 v[140:143], v247
	ds_read_b128 v[144:147], v247 offset:2048
	ds_read_b128 v[148:151], v247 offset:4096
	ds_read_b128 v[152:155], v247 offset:6144
	ds_read_b128 v[216:219], v247 offset:8192
	ds_read_b128 v[220:223], v247 offset:10240
	ds_read_b128 v[224:227], v247 offset:12288
	ds_read_b128 v[228:231], v247 offset:14336
	s_waitcnt lgkmcnt(0)
; template <int NH>
; __device__ void gemm_sample_rows(const Params& p, const u16* __restrict__ A, const u16* __restrict__ Bt,
;                                  const float* __restrict__ resid, float* __restrict__ outf, unsigned char* smem, const int rep) {
;     ...
;     for (int ks = 0; ks < 8; ++ks) {
;       bf16x8 af[4], bfr[4];
; #pragma unroll
;       for (int mf = 0; mf < 4; ++mf) af[mf] = *(const bf16x8*)(ap + (size_t)(mf * 16) * K + ks * 32);
; #pragma unroll
;       for (int nf = 0; nf < 4; ++nf) bfr[nf] = *(const bf16x8*)(bp + (size_t)(nf * 16) * K + ks * 32);
; #pragma unroll
;       for (int mf = 0; mf < 4; ++mf)
; #pragma unroll
;         for (int nf = 0; nf < 4; ++nf)
;           acc[mf][nf] = __builtin_amdgcn_mfma_f32_16x16x32_bf16(af[mf], bfr[nf], acc[mf][nf], 0, 0, 0);
;     }
	s_add_u32 m0, s54, 0x0
	s_nop 0
	global_load_lds_dwordx4 v232, s[50:51]
	s_add_u32 m0, s54, 0x400
	s_nop 0
	global_load_lds_dwordx4 v233, s[50:51]
	s_add_u32 m0, s54, 0x800
	s_nop 0
	global_load_lds_dwordx4 v234, s[50:51]
	s_add_u32 m0, s54, 0xc00
	s_nop 0
	global_load_lds_dwordx4 v235, s[50:51]
	s_add_u32 m0, s54, 0x1000
	s_nop 0
	global_load_lds_dwordx4 v236, s[50:51]
	s_add_u32 m0, s54, 0x1400
	s_nop 0
	global_load_lds_dwordx4 v237, s[50:51]
	s_add_u32 m0, s54, 0x1800
	s_nop 0
	global_load_lds_dwordx4 v238, s[50:51]
	s_add_u32 m0, s54, 0x1c00
	s_nop 0
	global_load_lds_dwordx4 v239, s[50:51]
	s_add_u32 m0, s54, 0x2000
	s_nop 0
	global_load_lds_dwordx4 v232, s[52:53]
	s_add_u32 m0, s54, 0x2400
	s_nop 0
	global_load_lds_dwordx4 v233, s[52:53]
	s_add_u32 m0, s54, 0x2800
	s_nop 0
	global_load_lds_dwordx4 v234, s[52:53]
	s_add_u32 m0, s54, 0x2c00
	s_nop 0
	global_load_lds_dwordx4 v235, s[52:53]
	s_add_u32 m0, s54, 0x3000
	s_nop 0
	global_load_lds_dwordx4 v236, s[52:53]
	s_add_u32 m0, s54, 0x3400
	s_nop 0
	global_load_lds_dwordx4 v237, s[52:53]
	s_add_u32 m0, s54, 0x3800
	s_nop 0
	global_load_lds_dwordx4 v238, s[52:53]
	s_add_u32 m0, s54, 0x3c00
	s_nop 0
	global_load_lds_dwordx4 v239, s[52:53]
	s_add_u32 s50, s50, 0x80
	s_addc_u32 s51, s51, 0
	s_add_u32 s52, s52, 0x80
	s_addc_u32 s53, s53, 0
	v_mfma_f32_16x16x32_bf16 v[60:63], v[124:127], v[200:203], v[60:63]
	v_mfma_f32_16x16x32_bf16 v[52:55], v[124:127], v[204:207], v[52:55]
	v_mfma_f32_16x16x32_bf16 v[48:51], v[124:127], v[208:211], v[48:51]
	v_mfma_f32_16x16x32_bf16 v[44:47], v[124:127], v[212:215], v[44:47]
	v_mfma_f32_16x16x32_bf16 v[40:43], v[128:131], v[200:203], v[40:43]
	v_mfma_f32_16x16x32_bf16 v[36:39], v[128:131], v[204:207], v[36:39]
	v_mfma_f32_16x16x32_bf16 v[20:23], v[128:131], v[208:211], v[20:23]
	v_mfma_f32_16x16x32_bf16 v[12:15], v[128:131], v[212:215], v[12:15]
	v_mfma_f32_16x16x32_bf16 v[16:19], v[132:135], v[200:203], v[16:19]
	v_mfma_f32_16x16x32_bf16 v[24:27], v[132:135], v[204:207], v[24:27]
	v_mfma_f32_16x16x32_bf16 v[28:31], v[132:135], v[208:211], v[28:31]
	v_mfma_f32_16x16x32_bf16 v[32:35], v[132:135], v[212:215], v[32:35]
	v_mfma_f32_16x16x32_bf16 v[0:3], v[136:139], v[200:203], v[0:3]
	v_mfma_f32_16x16x32_bf16 v[4:7], v[136:139], v[204:207], v[4:7]
	v_mfma_f32_16x16x32_bf16 v[8:11], v[136:139], v[208:211], v[8:11]
	v_mfma_f32_16x16x32_bf16 v[56:59], v[136:139], v[212:215], v[56:59]
	v_mfma_f32_16x16x32_bf16 v[60:63], v[140:143], v[216:219], v[60:63]
	v_mfma_f32_16x16x32_bf16 v[52:55], v[140:143], v[220:223], v[52:55]
	v_mfma_f32_16x16x32_bf16 v[48:51], v[140:143], v[224:227], v[48:51]
	v_mfma_f32_16x16x32_bf16 v[44:47], v[140:143], v[228:231], v[44:47]
	v_mfma_f32_16x16x32_bf16 v[40:43], v[144:147], v[216:219], v[40:43]
	v_mfma_f32_16x16x32_bf16 v[36:39], v[144:147], v[220:223], v[36:39]
	v_mfma_f32_16x16x32_bf16 v[20:23], v[144:147], v[224:227], v[20:23]
	v_mfma_f32_16x16x32_bf16 v[12:15], v[144:147], v[228:231], v[12:15]
	v_mfma_f32_16x16x32_bf16 v[16:19], v[148:151], v[216:219], v[16:19]
	v_mfma_f32_16x16x32_bf16 v[24:27], v[148:151], v[220:223], v[24:27]
	v_mfma_f32_16x16x32_bf16 v[28:31], v[148:151], v[224:227], v[28:31]
	v_mfma_f32_16x16x32_bf16 v[32:35], v[148:151], v[228:231], v[32:35]
	v_mfma_f32_16x16x32_bf16 v[0:3], v[152:155], v[216:219], v[0:3]
	v_mfma_f32_16x16x32_bf16 v[4:7], v[152:155], v[220:223], v[4:7]
	v_mfma_f32_16x16x32_bf16 v[8:11], v[152:155], v[224:227], v[8:11]
	v_mfma_f32_16x16x32_bf16 v[56:59], v[152:155], v[228:231], v[56:59]
	s_waitcnt vmcnt(0)
	ds_read_b128 v[124:127], v246
	ds_read_b128 v[128:131], v246 offset:2048
	ds_read_b128 v[132:135], v246 offset:4096
	ds_read_b128 v[136:139], v246 offset:6144
	ds_read_b128 v[200:203], v246 offset:8192
	ds_read_b128 v[204:207], v246 offset:10240
	ds_read_b128 v[208:211], v246 offset:12288
	ds_read_b128 v[212:215], v246 offset:14336
	ds_read_b128 v[140:143], v247
	ds_read_b128 v[144:147], v247 offset:2048
	ds_read_b128 v[148:151], v247 offset:4096
	ds_read_b128 v[152:155], v247 offset:6144
	ds_read_b128 v[216:219], v247 offset:8192
	ds_read_b128 v[220:223], v247 offset:10240
	ds_read_b128 v[224:227], v247 offset:12288
	ds_read_b128 v[228:231], v247 offset:14336
	s_waitcnt lgkmcnt(0)
	s_add_u32 m0, s54, 0x0
	s_nop 0
	global_load_lds_dwordx4 v232, s[50:51]
	s_add_u32 m0, s54, 0x400
	s_nop 0
	global_load_lds_dwordx4 v233, s[50:51]
	s_add_u32 m0, s54, 0x800
	s_nop 0
	global_load_lds_dwordx4 v234, s[50:51]
	s_add_u32 m0, s54, 0xc00
	s_nop 0
	global_load_lds_dwordx4 v235, s[50:51]
	s_add_u32 m0, s54, 0x1000
	s_nop 0
	global_load_lds_dwordx4 v236, s[50:51]
	s_add_u32 m0, s54, 0x1400
	s_nop 0
	global_load_lds_dwordx4 v237, s[50:51]
	s_add_u32 m0, s54, 0x1800
	s_nop 0
	global_load_lds_dwordx4 v238, s[50:51]
	s_add_u32 m0, s54, 0x1c00
	s_nop 0
	global_load_lds_dwordx4 v239, s[50:51]
	s_add_u32 m0, s54, 0x2000
	s_nop 0
	global_load_lds_dwordx4 v232, s[52:53]
	s_add_u32 m0, s54, 0x2400
	s_nop 0
	global_load_lds_dwordx4 v233, s[52:53]
	s_add_u32 m0, s54, 0x2800
	s_nop 0
	global_load_lds_dwordx4 v234, s[52:53]
	s_add_u32 m0, s54, 0x2c00
	s_nop 0
	global_load_lds_dwordx4 v235, s[52:53]
	s_add_u32 m0, s54, 0x3000
	s_nop 0
	global_load_lds_dwordx4 v236, s[52:53]
	s_add_u32 m0, s54, 0x3400
	s_nop 0
	global_load_lds_dwordx4 v237, s[52:53]
	s_add_u32 m0, s54, 0x3800
	s_nop 0
	global_load_lds_dwordx4 v238, s[52:53]
	s_add_u32 m0, s54, 0x3c00
	s_nop 0
	global_load_lds_dwordx4 v239, s[52:53]
	s_add_u32 s50, s50, 0x80
	s_addc_u32 s51, s51, 0
	s_add_u32 s52, s52, 0x80
	s_addc_u32 s53, s53, 0
	v_mfma_f32_16x16x32_bf16 v[60:63], v[124:127], v[200:203], v[60:63]
	v_mfma_f32_16x16x32_bf16 v[52:55], v[124:127], v[204:207], v[52:55]
; template <int NH>
; __device__ void gemm_sample_rows(const Params& p, const u16* __restrict__ A, const u16* __restrict__ Bt,
;                                  const float* __restrict__ resid, float* __restrict__ outf, unsigned char* smem, const int rep) {
;     ...
;     for (int ks = 0; ks < 8; ++ks) {
;       bf16x8 af[4], bfr[4];
; #pragma unroll
;       for (int mf = 0; mf < 4; ++mf) af[mf] = *(const bf16x8*)(ap + (size_t)(mf * 16) * K + ks * 32);
; #pragma unroll
;       for (int nf = 0; nf < 4; ++nf) bfr[nf] = *(const bf16x8*)(bp + (size_t)(nf * 16) * K + ks * 32);
; #pragma unroll
;       for (int mf = 0; mf < 4; ++mf)
; #pragma unroll
;         for (int nf = 0; nf < 4; ++nf)
;           acc[mf][nf] = __builtin_amdgcn_mfma_f32_16x16x32_bf16(af[mf], bfr[nf], acc[mf][nf], 0, 0, 0);
;     }
;     __syncthreads();
	v_mfma_f32_16x16x32_bf16 v[48:51], v[124:127], v[208:211], v[48:51]
	v_mfma_f32_16x16x32_bf16 v[44:47], v[124:127], v[212:215], v[44:47]
	v_mfma_f32_16x16x32_bf16 v[40:43], v[128:131], v[200:203], v[40:43]
	v_mfma_f32_16x16x32_bf16 v[36:39], v[128:131], v[204:207], v[36:39]
	v_mfma_f32_16x16x32_bf16 v[20:23], v[128:131], v[208:211], v[20:23]
	v_mfma_f32_16x16x32_bf16 v[12:15], v[128:131], v[212:215], v[12:15]
	v_mfma_f32_16x16x32_bf16 v[16:19], v[132:135], v[200:203], v[16:19]
	v_mfma_f32_16x16x32_bf16 v[24:27], v[132:135], v[204:207], v[24:27]
	v_mfma_f32_16x16x32_bf16 v[28:31], v[132:135], v[208:211], v[28:31]
	v_mfma_f32_16x16x32_bf16 v[32:35], v[132:135], v[212:215], v[32:35]
	v_mfma_f32_16x16x32_bf16 v[0:3], v[136:139], v[200:203], v[0:3]
	v_mfma_f32_16x16x32_bf16 v[4:7], v[136:139], v[204:207], v[4:7]
	v_mfma_f32_16x16x32_bf16 v[8:11], v[136:139], v[208:211], v[8:11]
	v_mfma_f32_16x16x32_bf16 v[56:59], v[136:139], v[212:215], v[56:59]
	v_mfma_f32_16x16x32_bf16 v[60:63], v[140:143], v[216:219], v[60:63]
	v_mfma_f32_16x16x32_bf16 v[52:55], v[140:143], v[220:223], v[52:55]
	v_mfma_f32_16x16x32_bf16 v[48:51], v[140:143], v[224:227], v[48:51]
	v_mfma_f32_16x16x32_bf16 v[44:47], v[140:143], v[228:231], v[44:47]
	v_mfma_f32_16x16x32_bf16 v[40:43], v[144:147], v[216:219], v[40:43]
	v_mfma_f32_16x16x32_bf16 v[36:39], v[144:147], v[220:223], v[36:39]
	v_mfma_f32_16x16x32_bf16 v[20:23], v[144:147], v[224:227], v[20:23]
	v_mfma_f32_16x16x32_bf16 v[12:15], v[144:147], v[228:231], v[12:15]
	v_mfma_f32_16x16x32_bf16 v[16:19], v[148:151], v[216:219], v[16:19]
	v_mfma_f32_16x16x32_bf16 v[24:27], v[148:151], v[220:223], v[24:27]
	v_mfma_f32_16x16x32_bf16 v[28:31], v[148:151], v[224:227], v[28:31]
	v_mfma_f32_16x16x32_bf16 v[32:35], v[148:151], v[228:231], v[32:35]
	v_mfma_f32_16x16x32_bf16 v[0:3], v[152:155], v[216:219], v[0:3]
	v_mfma_f32_16x16x32_bf16 v[4:7], v[152:155], v[220:223], v[4:7]
	v_mfma_f32_16x16x32_bf16 v[8:11], v[152:155], v[224:227], v[8:11]
	v_mfma_f32_16x16x32_bf16 v[56:59], v[152:155], v[228:231], v[56:59]
	s_waitcnt vmcnt(0)
	ds_read_b128 v[124:127], v246
	ds_read_b128 v[128:131], v246 offset:2048
	ds_read_b128 v[132:135], v246 offset:4096
	ds_read_b128 v[136:139], v246 offset:6144
	ds_read_b128 v[200:203], v246 offset:8192
	ds_read_b128 v[204:207], v246 offset:10240
	ds_read_b128 v[208:211], v246 offset:12288
	ds_read_b128 v[212:215], v246 offset:14336
	ds_read_b128 v[140:143], v247
	ds_read_b128 v[144:147], v247 offset:2048
	ds_read_b128 v[148:151], v247 offset:4096
	ds_read_b128 v[152:155], v247 offset:6144
	ds_read_b128 v[216:219], v247 offset:8192
	ds_read_b128 v[220:223], v247 offset:10240
	ds_read_b128 v[224:227], v247 offset:12288
	ds_read_b128 v[228:231], v247 offset:14336
	s_waitcnt lgkmcnt(0)
	v_mfma_f32_16x16x32_bf16 v[60:63], v[124:127], v[200:203], v[60:63]
	v_mfma_f32_16x16x32_bf16 v[52:55], v[124:127], v[204:207], v[52:55]
	v_mfma_f32_16x16x32_bf16 v[48:51], v[124:127], v[208:211], v[48:51]
	v_mfma_f32_16x16x32_bf16 v[44:47], v[124:127], v[212:215], v[44:47]
	v_mfma_f32_16x16x32_bf16 v[40:43], v[128:131], v[200:203], v[40:43]
	v_mfma_f32_16x16x32_bf16 v[36:39], v[128:131], v[204:207], v[36:39]
	v_mfma_f32_16x16x32_bf16 v[20:23], v[128:131], v[208:211], v[20:23]
	v_mfma_f32_16x16x32_bf16 v[12:15], v[128:131], v[212:215], v[12:15]
	v_mfma_f32_16x16x32_bf16 v[16:19], v[132:135], v[200:203], v[16:19]
	v_mfma_f32_16x16x32_bf16 v[24:27], v[132:135], v[204:207], v[24:27]
	v_mfma_f32_16x16x32_bf16 v[28:31], v[132:135], v[208:211], v[28:31]
	v_mfma_f32_16x16x32_bf16 v[32:35], v[132:135], v[212:215], v[32:35]
	v_mfma_f32_16x16x32_bf16 v[0:3], v[136:139], v[200:203], v[0:3]
	v_mfma_f32_16x16x32_bf16 v[4:7], v[136:139], v[204:207], v[4:7]
	v_mfma_f32_16x16x32_bf16 v[8:11], v[136:139], v[208:211], v[8:11]
	v_mfma_f32_16x16x32_bf16 v[56:59], v[136:139], v[212:215], v[56:59]
	v_mfma_f32_16x16x32_bf16 v[60:63], v[140:143], v[216:219], v[60:63]
	v_mfma_f32_16x16x32_bf16 v[52:55], v[140:143], v[220:223], v[52:55]
	v_mfma_f32_16x16x32_bf16 v[48:51], v[140:143], v[224:227], v[48:51]
	v_mfma_f32_16x16x32_bf16 v[44:47], v[140:143], v[228:231], v[44:47]
	v_mfma_f32_16x16x32_bf16 v[40:43], v[144:147], v[216:219], v[40:43]
	v_mfma_f32_16x16x32_bf16 v[36:39], v[144:147], v[220:223], v[36:39]
	v_mfma_f32_16x16x32_bf16 v[20:23], v[144:147], v[224:227], v[20:23]
	v_mfma_f32_16x16x32_bf16 v[12:15], v[144:147], v[228:231], v[12:15]
	v_mfma_f32_16x16x32_bf16 v[16:19], v[148:151], v[216:219], v[16:19]
	v_mfma_f32_16x16x32_bf16 v[24:27], v[148:151], v[220:223], v[24:27]
	v_mfma_f32_16x16x32_bf16 v[28:31], v[148:151], v[224:227], v[28:31]
	v_mfma_f32_16x16x32_bf16 v[32:35], v[148:151], v[228:231], v[32:35]
	v_mfma_f32_16x16x32_bf16 v[0:3], v[152:155], v[216:219], v[0:3]
	v_mfma_f32_16x16x32_bf16 v[4:7], v[152:155], v[220:223], v[4:7]
	v_mfma_f32_16x16x32_bf16 v[8:11], v[152:155], v[224:227], v[8:11]
	v_mfma_f32_16x16x32_bf16 v[56:59], v[152:155], v[228:231], v[56:59]
	s_movk_i32 s4, 0x200
	s_mov_b32 s5, 0
	s_cmpk_eq_i32 s4, 0x200
	s_waitcnt lgkmcnt(0)
	s_barrier
; template <int NH>
; __device__ void gemm_sample_rows(const Params& p, const u16* __restrict__ A, const u16* __restrict__ Bt,
;                                  const float* __restrict__ resid, float* __restrict__ outf, unsigned char* smem, const int rep) {
;     ...
;     __syncthreads();
;     {
;       const int h = (w * 256) / (K / NH);
; #pragma unroll
;       for (int mf = 0; mf < 4; ++mf)
; #pragma unroll
;         for (int r = 0; r < 4; ++r) {
;           const int row = mf * 16 + 4 * g + r;
;           const float sc = rstdS[row * NH + h];
; #pragma unroll
;           for (int nf = 0; nf < 4; ++nf) red[(w * 64 + row) * RS + nf * 16 + l15] = acc[mf][nf][r] * sc;
;         }
;     }
;     __syncthreads();
;     {
;       const int row = tid >> 3, c0 = (tid & 7) * 8;
;       float o[8];
;       const size_t gidx = (size_t)(m0 + row) * 1024 + n0 + c0;
	ds_read_b32 v66, v90
	s_add_i32 s15, s15, s16
	s_add_i32 s17, s17, s18
	s_waitcnt lgkmcnt(0)
	v_mul_f32_e32 v60, v60, v66
	v_mul_f32_e32 v52, v52, v66
	v_mul_f32_e32 v48, v48, v66
	v_mul_f32_e32 v44, v44, v66
	ds_write2_b32 v91, v60, v52 offset1:16
	ds_write2_b32 v91, v48, v44 offset0:32 offset1:48
	ds_read_b32 v44, v92
	s_waitcnt lgkmcnt(0)
	v_mul_f32_e32 v48, v61, v44
	v_mul_f32_e32 v52, v53, v44
	ds_write2_b32 v93, v48, v52 offset1:16
	v_mul_f32_e32 v48, v49, v44
	v_mul_f32_e32 v44, v45, v44
	ds_write2_b32 v93, v48, v44 offset0:32 offset1:48
	ds_read_b32 v44, v94
	s_waitcnt lgkmcnt(0)
	v_mul_f32_e32 v45, v62, v44
	v_mul_f32_e32 v48, v54, v44
	ds_write2_b32 v95, v45, v48 offset1:16
	v_mul_f32_e32 v45, v50, v44
	v_mul_f32_e32 v44, v46, v44
	ds_write2_b32 v95, v45, v44 offset0:32 offset1:48
	ds_read_b32 v44, v96
	s_waitcnt lgkmcnt(0)
	v_mul_f32_e32 v45, v63, v44
	v_mul_f32_e32 v46, v55, v44
	ds_write2_b32 v97, v45, v46 offset1:16
	v_mul_f32_e32 v45, v51, v44
	v_mul_f32_e32 v44, v47, v44
	ds_write2_b32 v97, v45, v44 offset0:32 offset1:48
	ds_read_b32 v44, v98
	s_waitcnt lgkmcnt(0)
	v_mul_f32_e32 v40, v40, v44
	v_mul_f32_e32 v36, v36, v44
	v_mul_f32_e32 v20, v20, v44
	v_mul_f32_e32 v12, v12, v44
	ds_write2_b32 v99, v40, v36 offset1:16
	ds_write2_b32 v99, v20, v12 offset0:32 offset1:48
	ds_read_b32 v12, v100
	v_add_u32_e32 v40, 0xc318, v70
	s_waitcnt lgkmcnt(0)
	v_mul_f32_e32 v20, v41, v12
	v_mul_f32_e32 v36, v37, v12
	ds_write2_b32 v101, v20, v36 offset1:16
	v_mul_f32_e32 v20, v21, v12
	v_mul_f32_e32 v12, v13, v12
	ds_write2_b32 v101, v20, v12 offset0:32 offset1:48
	ds_read_b32 v12, v102
	v_add_u32_e32 v36, 0x4118, v70
	s_waitcnt lgkmcnt(0)
	v_mul_f32_e32 v13, v42, v12
	v_mul_f32_e32 v20, v38, v12
	ds_write2_b32 v103, v13, v20 offset1:16
	v_mul_f32_e32 v13, v22, v12
	v_mul_f32_e32 v12, v14, v12
	ds_write2_b32 v103, v13, v12 offset0:32 offset1:48
	ds_read_b32 v12, v104
	v_add_u32_e32 v20, 0xc308, v70
	v_add_u32_e32 v22, 0x4110, v70
	v_add_u32_e32 v38, 0x8218, v70
	s_waitcnt lgkmcnt(0)
	v_mul_f32_e32 v13, v43, v12
	v_mul_f32_e32 v14, v39, v12
	ds_write2_b32 v105, v13, v14 offset1:16
	v_mul_f32_e32 v13, v23, v12
	v_mul_f32_e32 v12, v15, v12
	ds_write2_b32 v105, v13, v12 offset0:32 offset1:48
	ds_read_b32 v12, v106
	s_waitcnt lgkmcnt(0)
	v_mul_f32_e32 v13, v16, v12
	v_mul_f32_e32 v14, v24, v12
	ds_write2_b32 v107, v13, v14 offset1:16
	v_mul_f32_e32 v13, v28, v12
	v_mul_f32_e32 v12, v32, v12
	ds_write2_b32 v107, v13, v12 offset0:32 offset1:48
	ds_read_b32 v12, v108
	v_add_u32_e32 v16, 0x4108, v70
	v_add_u32_e32 v24, 0x8210, v70
	s_waitcnt lgkmcnt(0)
	v_mul_f32_e32 v13, v17, v12
	v_mul_f32_e32 v14, v25, v12
	ds_write2_b32 v109, v13, v14 offset1:16
	v_mul_f32_e32 v13, v29, v12
	v_mul_f32_e32 v12, v33, v12
	ds_write2_b32 v109, v13, v12 offset0:32 offset1:48
	ds_read_b32 v12, v110
	s_waitcnt lgkmcnt(0)
	v_mul_f32_e32 v13, v18, v12
	v_mul_f32_e32 v14, v26, v12
	ds_write2_b32 v111, v13, v14 offset1:16
	v_mul_f32_e32 v13, v30, v12
	v_mul_f32_e32 v12, v34, v12
	ds_write2_b32 v111, v13, v12 offset0:32 offset1:48
	ds_read_b32 v12, v112
	v_add_u32_e32 v18, 0x8208, v70
	v_add_u32_e32 v34, 0xc310, v70
	s_waitcnt lgkmcnt(0)
	v_mul_f32_e32 v13, v19, v12
	v_mul_f32_e32 v14, v27, v12
	ds_write2_b32 v113, v13, v14 offset1:16
	v_mul_f32_e32 v13, v31, v12
	v_mul_f32_e32 v12, v35, v12
	ds_write2_b32 v113, v13, v12 offset0:32 offset1:48
	ds_read_b32 v12, v114
	v_add_u32_e32 v14, 0xc300, v70
	s_waitcnt lgkmcnt(0)
	v_mul_f32_e32 v0, v0, v12
	v_mul_f32_e32 v4, v4, v12
	ds_write2_b32 v115, v0, v4 offset1:16
	v_mul_f32_e32 v0, v8, v12
	v_mul_f32_e32 v4, v56, v12
	ds_write2_b32 v115, v0, v4 offset0:32 offset1:48
	ds_read_b32 v0, v116
	v_add_u32_e32 v12, 0x8200, v70
	s_waitcnt lgkmcnt(0)
	v_mul_f32_e32 v1, v1, v0
	v_mul_f32_e32 v4, v5, v0
	ds_write2_b32 v117, v1, v4 offset1:16
	v_mul_f32_e32 v1, v9, v0
	v_mul_f32_e32 v0, v57, v0
	ds_write2_b32 v117, v1, v0 offset0:32 offset1:48
	ds_read_b32 v0, v118
	s_waitcnt lgkmcnt(0)
	v_mul_f32_e32 v1, v2, v0
	v_mul_f32_e32 v2, v6, v0
	ds_write2_b32 v119, v1, v2 offset1:16
	v_mul_f32_e32 v1, v10, v0
	v_mul_f32_e32 v0, v58, v0
	ds_write2_b32 v119, v1, v0 offset0:32 offset1:48
	ds_read_b32 v0, v120
	v_add_u32_e32 v10, 0x4100, v70
	s_waitcnt lgkmcnt(0)
	v_mul_f32_e32 v1, v3, v0
	v_mul_f32_e32 v2, v7, v0
	ds_write2_b32 v121, v1, v2 offset1:16
	v_mul_f32_e32 v1, v11, v0
	v_mul_f32_e32 v0, v59, v0
	ds_write2_b32 v121, v1, v0 offset0:32 offset1:48
	v_add_u32_e32 v0, s0, v197
	v_ashrrev_i32_e32 v1, 31, v0
	v_lshlrev_b64 v[0:1], 12, v[0:1]
	s_lshl_b32 s0, s29, 8
	v_lshl_add_u64 v[0:1], s[10:11], 0, v[0:1]
	s_and_b32 s0, s0, 0xf00
	v_lshl_add_u64 v[0:1], v[0:1], 0, s[0:1]
	v_lshl_add_u64 v[8:9], v[0:1], 0, v[180:181]
	s_waitcnt lgkmcnt(0)
	s_barrier
; template <int NH>
; __device__ void gemm_sample_rows(const Params& p, const u16* __restrict__ A, const u16* __restrict__ Bt,
;                                  const float* __restrict__ resid, float* __restrict__ outf, unsigned char* smem, const int rep) {
;     ...
;     {
;       const int row = tid >> 3, c0 = (tid & 7) * 8;
;       float o[8];
;       const size_t gidx = (size_t)(m0 + row) * 1024 + n0 + c0;
;       const float* rp = resid ? resid + gidx : p.x_sample + (size_t)(m0 - NPROMPT + row) * 1024 + n0 + c0;
;       const float4 r0 = *(const float4*)rp, r1 = *(const float4*)(rp + 4);
;       o[0] = r0.x; o[1] = r0.y; o[2] = r0.z; o[3] = r0.w; o[4] = r1.x; o[5] = r1.y; o[6] = r1.z; o[7] = r1.w;
; #pragma unroll
;       for (int ww = 0; ww < 8; ++ww)
; #pragma unroll
;         for (int j = 0; j < 8; ++j) o[j] += red[(ww * 64 + row) * RS + c0 + j];
;       *(float4*)(outf + gidx) = make_float4(o[0], o[1], o[2], o[3]);
;       *(float4*)(outf + gidx + 4) = make_float4(o[4], o[5], o[6], o[7]);
;     }
;     __syncthreads();
	global_load_dwordx4 v[0:3], v[8:9], off
	global_load_dwordx4 v[4:7], v[8:9], off offset:16
	ds_read2_b32 v[10:11], v10 offset1:1
	ds_read2_b32 v[12:13], v12 offset1:1
	ds_read2_b32 v[14:15], v14 offset1:1
	ds_read2_b32 v[16:17], v16 offset1:1
	ds_read2_b32 v[18:19], v18 offset1:1
	ds_read2_b32 v[20:21], v20 offset1:1
	ds_read2_b32 v[22:23], v22 offset1:1
	ds_read2_b32 v[24:25], v24 offset1:1
	ds_read2_b32 v[26:27], v70 offset1:1
	ds_read2_b32 v[28:29], v70 offset0:2 offset1:3
	ds_read2_b32 v[30:31], v70 offset0:4 offset1:5
	ds_read2_b32 v[32:33], v70 offset0:6 offset1:7
	ds_read2_b32 v[34:35], v34 offset1:1
	ds_read2_b32 v[36:37], v36 offset1:1
	ds_read2_b32 v[38:39], v38 offset1:1
	ds_read2_b32 v[40:41], v40 offset1:1
	ds_read2_b32 v[42:43], v71 offset1:1
	ds_read2_b32 v[44:45], v72 offset1:1
	ds_read2_b32 v[46:47], v73 offset1:1
	ds_read2_b32 v[48:49], v74 offset1:1
	ds_read2_b32 v[50:51], v75 offset1:1
	ds_read2_b32 v[52:53], v76 offset1:1
	ds_read2_b32 v[54:55], v77 offset1:1
	ds_read2_b32 v[56:57], v78 offset1:1
	ds_read2_b32 v[58:59], v79 offset1:1
	ds_read2_b32 v[60:61], v80 offset1:1
	ds_read2_b32 v[62:63], v81 offset1:1
	ds_read2_b32 v[66:67], v82 offset1:1
	ds_read2_b32 v[68:69], v83 offset1:1
	ds_read2_b32 v[124:125], v84 offset1:1
	ds_read2_b32 v[126:127], v85 offset1:1
	ds_read2_b32 v[128:129], v86 offset1:1
	v_add_u32_e32 v8, s30, v197
	v_ashrrev_i32_e32 v9, 31, v8
	v_lshlrev_b64 v[8:9], 12, v[8:9]
	v_lshl_add_u64 v[8:9], s[6:7], 0, v[8:9]
	v_lshl_add_u64 v[8:9], v[8:9], 0, s[0:1]
	v_lshl_add_u64 v[8:9], v[8:9], 0, v[180:181]
	s_add_i32 s29, s29, s96
	s_cmp_ge_i32 s29, s14
	s_waitcnt vmcnt(1) lgkmcnt(14)
	v_pk_add_f32 v[0:1], v[0:1], v[26:27]
	v_pk_add_f32 v[2:3], v[2:3], v[28:29]
	v_pk_add_f32 v[0:1], v[0:1], v[10:11]
	v_pk_add_f32 v[2:3], v[2:3], v[16:17]
	v_pk_add_f32 v[0:1], v[0:1], v[12:13]
	v_pk_add_f32 v[2:3], v[2:3], v[18:19]
	v_pk_add_f32 v[0:1], v[0:1], v[14:15]
	v_pk_add_f32 v[2:3], v[2:3], v[20:21]
	v_pk_add_f32 v[0:1], v[0:1], v[42:43]
	v_pk_add_f32 v[2:3], v[2:3], v[44:45]
	s_waitcnt lgkmcnt(11)
	v_pk_add_f32 v[0:1], v[0:1], v[50:51]
	s_waitcnt lgkmcnt(10)
	v_pk_add_f32 v[2:3], v[2:3], v[52:53]
	s_waitcnt lgkmcnt(7)
	v_pk_add_f32 v[0:1], v[0:1], v[58:59]
	s_waitcnt lgkmcnt(6)
	v_pk_add_f32 v[2:3], v[2:3], v[60:61]
	s_waitcnt lgkmcnt(3)
	v_pk_add_f32 v[0:1], v[0:1], v[68:69]
	s_waitcnt lgkmcnt(2)
	v_pk_add_f32 v[2:3], v[2:3], v[124:125]
	s_waitcnt vmcnt(0)
	v_pk_add_f32 v[4:5], v[4:5], v[30:31]
	global_store_dwordx4 v[8:9], v[0:3], off
	v_pk_add_f32 v[4:5], v[4:5], v[22:23]
	s_nop 0
	v_pk_add_f32 v[2:3], v[6:7], v[32:33]
	v_pk_add_f32 v[4:5], v[4:5], v[24:25]
	v_pk_add_f32 v[2:3], v[2:3], v[36:37]
	v_pk_add_f32 v[4:5], v[4:5], v[34:35]
	v_pk_add_f32 v[2:3], v[2:3], v[38:39]
	v_pk_add_f32 v[4:5], v[4:5], v[46:47]
	v_pk_add_f32 v[2:3], v[2:3], v[40:41]
	v_pk_add_f32 v[0:1], v[4:5], v[54:55]
	v_pk_add_f32 v[2:3], v[2:3], v[48:49]
	v_pk_add_f32 v[0:1], v[0:1], v[62:63]
	v_pk_add_f32 v[2:3], v[2:3], v[56:57]
	s_waitcnt lgkmcnt(1)
	v_pk_add_f32 v[0:1], v[0:1], v[126:127]
	v_pk_add_f32 v[2:3], v[2:3], v[66:67]
	s_waitcnt lgkmcnt(0)
	v_pk_add_f32 v[2:3], v[2:3], v[128:129]
	global_store_dwordx4 v[8:9], v[0:3], off offset:16
	s_barrier
	s_cbranch_scc0 .LBB0_726

; template <int NH>
; __device__ void gemm_sample_rows(const Params& p, const u16* __restrict__ A, const u16* __restrict__ Bt,
;                                  const float* __restrict__ resid, float* __restrict__ outf, unsigned char* smem, const int rep) {
;     ...
;   for (int item0 = blockIdx.x; item0 < 256 * rep; item0 += gridDim.x) {
;     const int item = item0 & 255;
;     const int m0 = NPROMPT + (item >> 4) * 64, n0 = (item & 15) * 64;
;     for (int idx = tid; idx < 64 * NH; idx += NTHR) {
;       const int row = idx / NH, h = idx % NH;
;       const float* pp = parts + (size_t)(m0 + row) * 64 + h * (64 / NH);
;       float sm = 0.f;
; #pragma unroll
;       for (int q = 0; q < 64 / NH; ++q) sm += pp[q];
;       rstdS[idx] = rsqrtf(sm / (float)(K / NH) + 1e-6f);
;     }
;     f32x4 acc[4][4];
; #pragma unroll
;     for (int i = 0; i < 4; ++i)
; #pragma unroll
;       for (int j = 0; j < 4; ++j) acc[i][j] = (f32x4){0.f, 0.f, 0.f, 0.f};
;     const u16* ap = A + (size_t)(m0 + l15) * K + w * 256 + 8 * g;
;     const u16* bp = Bt + (size_t)(n0 + l15) * K + w * 256 + 8 * g;
.Lsrmap8:
.LBB0_2031:
	s_lshr_b32 s55, s26, 4
	s_and_b32 s55, s55, 15
	s_lshl_b32 s55, s55, 18
	s_add_u32 s55, s55, 0x15262000
	v_readlane_b32 s54, v255, 6
	s_lshl_b32 s56, s54, 9
	s_add_u32 s55, s55, s56
	s_add_u32 s50, s84, s55
	s_addc_u32 s51, s85, 0
	s_and_b32 s55, s26, 15
	s_lshl_b32 s55, s55, 18
	s_add_u32 s55, s55, 0x1c40000
	s_add_u32 s55, s55, s56
	s_add_u32 s52, s84, s55
	s_addc_u32 s53, s85, 0
	s_lshl_b32 s54, s54, 14
	v_mbcnt_lo_u32_b32 v240, -1, 0
	v_mbcnt_hi_u32_b32 v240, -1, v240
	v_lshrrev_b32_e32 v241, 3, v240
	v_lshlrev_b32_e32 v241, 12, v241
	v_and_b32_e32 v242, 7, v240
	v_lshrrev_b32_e32 v243, 4, v240
	v_xor_b32_e32 v244, v242, v243
	v_lshl_add_u32 v232, v244, 4, v241
	v_xor_b32_e32 v244, 4, v244
	v_lshl_add_u32 v233, v244, 4, v241
	v_add_u32_e32 v233, 0x8000, v233
	v_add_u32_e32 v234, 0x10000, v232
	v_add_u32_e32 v235, 0x10000, v233
	v_add_u32_e32 v236, 0x20000, v232
	v_add_u32_e32 v237, 0x20000, v233
	v_add_u32_e32 v238, 0x30000, v232
	v_add_u32_e32 v239, 0x30000, v233
	v_and_b32_e32 v245, 15, v240
	v_lshrrev_b32_e32 v246, 1, v245
	v_xor_b32_e32 v246, v243, v246
	v_lshlrev_b32_e32 v246, 4, v246
	v_lshl_add_u32 v246, v245, 7, v246
	v_add_u32_e32 v246, s54, v246
	v_xor_b32_e32 v247, 64, v246
	s_add_u32 m0, s54, 0x0
	s_nop 0
	global_load_lds_dwordx4 v232, s[50:51]
	s_add_u32 m0, s54, 0x400
	s_nop 0
	global_load_lds_dwordx4 v233, s[50:51]
	s_add_u32 m0, s54, 0x800
	s_nop 0
	global_load_lds_dwordx4 v234, s[50:51]
	s_add_u32 m0, s54, 0xc00
	s_nop 0
	global_load_lds_dwordx4 v235, s[50:51]
	s_add_u32 m0, s54, 0x1000
	s_nop 0
	global_load_lds_dwordx4 v236, s[50:51]
	s_add_u32 m0, s54, 0x1400
	s_nop 0
	global_load_lds_dwordx4 v237, s[50:51]
	s_add_u32 m0, s54, 0x1800
	s_nop 0
	global_load_lds_dwordx4 v238, s[50:51]
	s_add_u32 m0, s54, 0x1c00
	s_nop 0
	global_load_lds_dwordx4 v239, s[50:51]
	s_add_u32 m0, s54, 0x2000
	s_nop 0
	global_load_lds_dwordx4 v232, s[52:53]
	s_add_u32 m0, s54, 0x2400
	s_nop 0
	global_load_lds_dwordx4 v233, s[52:53]
	s_add_u32 m0, s54, 0x2800
	s_nop 0
	global_load_lds_dwordx4 v234, s[52:53]
	s_add_u32 m0, s54, 0x2c00
	s_nop 0
	global_load_lds_dwordx4 v235, s[52:53]
	s_add_u32 m0, s54, 0x3000
	s_nop 0
	global_load_lds_dwordx4 v236, s[52:53]
	s_add_u32 m0, s54, 0x3400
	s_nop 0
	global_load_lds_dwordx4 v237, s[52:53]
	s_add_u32 m0, s54, 0x3800
	s_nop 0
	global_load_lds_dwordx4 v238, s[52:53]
	s_add_u32 m0, s54, 0x3c00
	s_nop 0
	global_load_lds_dwordx4 v239, s[52:53]
	s_add_u32 s50, s50, 0x80
	s_addc_u32 s51, s51, 0
	s_add_u32 s52, s52, 0x80
	s_addc_u32 s53, s53, 0
	s_lshl_b32 s0, s26, 2
	s_and_b32 s27, s0, 0x3c0
	s_bitset1_b32 s27, 14
	s_and_saveexec_b64 s[0:1], vcc
	s_cbranch_execz .LBB0_2034
	s_mov_b64 s[4:5], 0
	v_mov_b32_e32 v0, v123
	v_mov_b32_e32 v1, v198
	v_mov_b32_e32 v2, v196

; template <int NH>
; __device__ void gemm_sample_rows(const Params& p, const u16* __restrict__ A, const u16* __restrict__ Bt,
;                                  const float* __restrict__ resid, float* __restrict__ outf, unsigned char* smem, const int rep) {
;     ...
;     const u16* ap = A + (size_t)(m0 + l15) * K + w * 256 + 8 * g;
;     const u16* bp = Bt + (size_t)(n0 + l15) * K + w * 256 + 8 * g;
; #pragma unroll 2
;     for (int ks = 0; ks < 8; ++ks) {
;       bf16x8 af[4], bfr[4];
; #pragma unroll
;       for (int mf = 0; mf < 4; ++mf) af[mf] = *(const bf16x8*)(ap + (size_t)(mf * 16) * K + ks * 32);
; #pragma unroll
;       for (int nf = 0; nf < 4; ++nf) bfr[nf] = *(const bf16x8*)(bp + (size_t)(nf * 16) * K + ks * 32);
; #pragma unroll
;       for (int mf = 0; mf < 4; ++mf)
; #pragma unroll
;         for (int nf = 0; nf < 4; ++nf)
;           acc[mf][nf] = __builtin_amdgcn_mfma_f32_16x16x32_bf16(af[mf], bfr[nf], acc[mf][nf], 0, 0, 0);
;     }
.LBB0_2035:
	s_waitcnt vmcnt(0)
	ds_read_b128 v[124:127], v246
	ds_read_b128 v[128:131], v246 offset:2048
	ds_read_b128 v[132:135], v246 offset:4096
	ds_read_b128 v[136:139], v246 offset:6144
	ds_read_b128 v[200:203], v246 offset:8192
	ds_read_b128 v[204:207], v246 offset:10240
	ds_read_b128 v[208:211], v246 offset:12288
	ds_read_b128 v[212:215], v246 offset:14336
	ds_read_b128 v[140:143], v247
	ds_read_b128 v[144:147], v247 offset:2048
	ds_read_b128 v[148:151], v247 offset:4096
	ds_read_b128 v[152:155], v247 offset:6144
	ds_read_b128 v[216:219], v247 offset:8192
	ds_read_b128 v[220:223], v247 offset:10240
	ds_read_b128 v[224:227], v247 offset:12288
	ds_read_b128 v[228:231], v247 offset:14336
	s_waitcnt lgkmcnt(0)
	s_add_u32 m0, s54, 0x0
	s_nop 0
	global_load_lds_dwordx4 v232, s[50:51]
	s_add_u32 m0, s54, 0x400
	s_nop 0
	global_load_lds_dwordx4 v233, s[50:51]
	s_add_u32 m0, s54, 0x800
	s_nop 0
	global_load_lds_dwordx4 v234, s[50:51]
	s_add_u32 m0, s54, 0xc00
	s_nop 0
	global_load_lds_dwordx4 v235, s[50:51]
	s_add_u32 m0, s54, 0x1000
	s_nop 0
	global_load_lds_dwordx4 v236, s[50:51]
	s_add_u32 m0, s54, 0x1400
	s_nop 0
	global_load_lds_dwordx4 v237, s[50:51]
	s_add_u32 m0, s54, 0x1800
	s_nop 0
	global_load_lds_dwordx4 v238, s[50:51]
	s_add_u32 m0, s54, 0x1c00
	s_nop 0
	global_load_lds_dwordx4 v239, s[50:51]
	s_add_u32 m0, s54, 0x2000
	s_nop 0
	global_load_lds_dwordx4 v232, s[52:53]
	s_add_u32 m0, s54, 0x2400
	s_nop 0
	global_load_lds_dwordx4 v233, s[52:53]
	s_add_u32 m0, s54, 0x2800
	s_nop 0
	global_load_lds_dwordx4 v234, s[52:53]
	s_add_u32 m0, s54, 0x2c00
	s_nop 0
	global_load_lds_dwordx4 v235, s[52:53]
	s_add_u32 m0, s54, 0x3000
	s_nop 0
	global_load_lds_dwordx4 v236, s[52:53]
	s_add_u32 m0, s54, 0x3400
	s_nop 0
	global_load_lds_dwordx4 v237, s[52:53]
	s_add_u32 m0, s54, 0x3800
	s_nop 0
	global_load_lds_dwordx4 v238, s[52:53]
	s_add_u32 m0, s54, 0x3c00
	s_nop 0
	global_load_lds_dwordx4 v239, s[52:53]
	s_add_u32 s50, s50, 0x80
	s_addc_u32 s51, s51, 0
	s_add_u32 s52, s52, 0x80
	s_addc_u32 s53, s53, 0
	v_mfma_f32_16x16x32_bf16 v[60:63], v[124:127], v[200:203], v[60:63]
	v_mfma_f32_16x16x32_bf16 v[56:59], v[124:127], v[204:207], v[56:59]
	v_mfma_f32_16x16x32_bf16 v[48:51], v[124:127], v[208:211], v[48:51]
	v_mfma_f32_16x16x32_bf16 v[44:47], v[124:127], v[212:215], v[44:47]
	v_mfma_f32_16x16x32_bf16 v[40:43], v[128:131], v[200:203], v[40:43]
	v_mfma_f32_16x16x32_bf16 v[36:39], v[128:131], v[204:207], v[36:39]
	v_mfma_f32_16x16x32_bf16 v[20:23], v[128:131], v[208:211], v[20:23]
	v_mfma_f32_16x16x32_bf16 v[12:15], v[128:131], v[212:215], v[12:15]
	v_mfma_f32_16x16x32_bf16 v[16:19], v[132:135], v[200:203], v[16:19]
	v_mfma_f32_16x16x32_bf16 v[24:27], v[132:135], v[204:207], v[24:27]
	v_mfma_f32_16x16x32_bf16 v[28:31], v[132:135], v[208:211], v[28:31]
	v_mfma_f32_16x16x32_bf16 v[32:35], v[132:135], v[212:215], v[32:35]
	v_mfma_f32_16x16x32_bf16 v[0:3], v[136:139], v[200:203], v[0:3]
	v_mfma_f32_16x16x32_bf16 v[4:7], v[136:139], v[204:207], v[4:7]
	v_mfma_f32_16x16x32_bf16 v[8:11], v[136:139], v[208:211], v[8:11]
	v_mfma_f32_16x16x32_bf16 v[52:55], v[136:139], v[212:215], v[52:55]
	v_mfma_f32_16x16x32_bf16 v[60:63], v[140:143], v[216:219], v[60:63]
	v_mfma_f32_16x16x32_bf16 v[56:59], v[140:143], v[220:223], v[56:59]
	v_mfma_f32_16x16x32_bf16 v[48:51], v[140:143], v[224:227], v[48:51]
	v_mfma_f32_16x16x32_bf16 v[44:47], v[140:143], v[228:231], v[44:47]
	v_mfma_f32_16x16x32_bf16 v[40:43], v[144:147], v[216:219], v[40:43]
	v_mfma_f32_16x16x32_bf16 v[36:39], v[144:147], v[220:223], v[36:39]
	v_mfma_f32_16x16x32_bf16 v[20:23], v[144:147], v[224:227], v[20:23]
	v_mfma_f32_16x16x32_bf16 v[12:15], v[144:147], v[228:231], v[12:15]
	v_mfma_f32_16x16x32_bf16 v[16:19], v[148:151], v[216:219], v[16:19]
	v_mfma_f32_16x16x32_bf16 v[24:27], v[148:151], v[220:223], v[24:27]
	v_mfma_f32_16x16x32_bf16 v[28:31], v[148:151], v[224:227], v[28:31]
	v_mfma_f32_16x16x32_bf16 v[32:35], v[148:151], v[228:231], v[32:35]
	v_mfma_f32_16x16x32_bf16 v[0:3], v[152:155], v[216:219], v[0:3]
	v_mfma_f32_16x16x32_bf16 v[4:7], v[152:155], v[220:223], v[4:7]
	v_mfma_f32_16x16x32_bf16 v[8:11], v[152:155], v[224:227], v[8:11]
	v_mfma_f32_16x16x32_bf16 v[52:55], v[152:155], v[228:231], v[52:55]
	s_waitcnt vmcnt(0)
	ds_read_b128 v[124:127], v246
	ds_read_b128 v[128:131], v246 offset:2048
	ds_read_b128 v[132:135], v246 offset:4096
	ds_read_b128 v[136:139], v246 offset:6144
	ds_read_b128 v[200:203], v246 offset:8192
	ds_read_b128 v[204:207], v246 offset:10240
	ds_read_b128 v[208:211], v246 offset:12288
	ds_read_b128 v[212:215], v246 offset:14336
	ds_read_b128 v[140:143], v247
	ds_read_b128 v[144:147], v247 offset:2048
	ds_read_b128 v[148:151], v247 offset:4096
	ds_read_b128 v[152:155], v247 offset:6144
	ds_read_b128 v[216:219], v247 offset:8192
	ds_read_b128 v[220:223], v247 offset:10240
	ds_read_b128 v[224:227], v247 offset:12288
	ds_read_b128 v[228:231], v247 offset:14336
	s_waitcnt lgkmcnt(0)
; template <int NH>
; __device__ void gemm_sample_rows(const Params& p, const u16* __restrict__ A, const u16* __restrict__ Bt,
;                                  const float* __restrict__ resid, float* __restrict__ outf, unsigned char* smem, const int rep) {
;     ...
;     for (int ks = 0; ks < 8; ++ks) {
;       bf16x8 af[4], bfr[4];
; #pragma unroll
;       for (int mf = 0; mf < 4; ++mf) af[mf] = *(const bf16x8*)(ap + (size_t)(mf * 16) * K + ks * 32);
; #pragma unroll
;       for (int nf = 0; nf < 4; ++nf) bfr[nf] = *(const bf16x8*)(bp + (size_t)(nf * 16) * K + ks * 32);
; #pragma unroll
;       for (int mf = 0; mf < 4; ++mf)
; #pragma unroll
;         for (int nf = 0; nf < 4; ++nf)
;           acc[mf][nf] = __builtin_amdgcn_mfma_f32_16x16x32_bf16(af[mf], bfr[nf], acc[mf][nf], 0, 0, 0);
;     }
	s_add_u32 m0, s54, 0x0
	s_nop 0
	global_load_lds_dwordx4 v232, s[50:51]
	s_add_u32 m0, s54, 0x400
	s_nop 0
	global_load_lds_dwordx4 v233, s[50:51]
	s_add_u32 m0, s54, 0x800
	s_nop 0
	global_load_lds_dwordx4 v234, s[50:51]
	s_add_u32 m0, s54, 0xc00
	s_nop 0
	global_load_lds_dwordx4 v235, s[50:51]
	s_add_u32 m0, s54, 0x1000
	s_nop 0
	global_load_lds_dwordx4 v236, s[50:51]
	s_add_u32 m0, s54, 0x1400
	s_nop 0
	global_load_lds_dwordx4 v237, s[50:51]
	s_add_u32 m0, s54, 0x1800
	s_nop 0
	global_load_lds_dwordx4 v238, s[50:51]
	s_add_u32 m0, s54, 0x1c00
	s_nop 0
	global_load_lds_dwordx4 v239, s[50:51]
	s_add_u32 m0, s54, 0x2000
	s_nop 0
	global_load_lds_dwordx4 v232, s[52:53]
	s_add_u32 m0, s54, 0x2400
	s_nop 0
	global_load_lds_dwordx4 v233, s[52:53]
	s_add_u32 m0, s54, 0x2800
	s_nop 0
	global_load_lds_dwordx4 v234, s[52:53]
	s_add_u32 m0, s54, 0x2c00
	s_nop 0
	global_load_lds_dwordx4 v235, s[52:53]
	s_add_u32 m0, s54, 0x3000
	s_nop 0
	global_load_lds_dwordx4 v236, s[52:53]
	s_add_u32 m0, s54, 0x3400
	s_nop 0
	global_load_lds_dwordx4 v237, s[52:53]
	s_add_u32 m0, s54, 0x3800
	s_nop 0
	global_load_lds_dwordx4 v238, s[52:53]
	s_add_u32 m0, s54, 0x3c00
	s_nop 0
	global_load_lds_dwordx4 v239, s[52:53]
	s_add_u32 s50, s50, 0x80
	s_addc_u32 s51, s51, 0
	s_add_u32 s52, s52, 0x80
	s_addc_u32 s53, s53, 0
	v_mfma_f32_16x16x32_bf16 v[60:63], v[124:127], v[200:203], v[60:63]
	v_mfma_f32_16x16x32_bf16 v[56:59], v[124:127], v[204:207], v[56:59]
	v_mfma_f32_16x16x32_bf16 v[48:51], v[124:127], v[208:211], v[48:51]
	v_mfma_f32_16x16x32_bf16 v[44:47], v[124:127], v[212:215], v[44:47]
	v_mfma_f32_16x16x32_bf16 v[40:43], v[128:131], v[200:203], v[40:43]
	v_mfma_f32_16x16x32_bf16 v[36:39], v[128:131], v[204:207], v[36:39]
	v_mfma_f32_16x16x32_bf16 v[20:23], v[128:131], v[208:211], v[20:23]
	v_mfma_f32_16x16x32_bf16 v[12:15], v[128:131], v[212:215], v[12:15]
	v_mfma_f32_16x16x32_bf16 v[16:19], v[132:135], v[200:203], v[16:19]
	v_mfma_f32_16x16x32_bf16 v[24:27], v[132:135], v[204:207], v[24:27]
	v_mfma_f32_16x16x32_bf16 v[28:31], v[132:135], v[208:211], v[28:31]
	v_mfma_f32_16x16x32_bf16 v[32:35], v[132:135], v[212:215], v[32:35]
	v_mfma_f32_16x16x32_bf16 v[0:3], v[136:139], v[200:203], v[0:3]
	v_mfma_f32_16x16x32_bf16 v[4:7], v[136:139], v[204:207], v[4:7]
	v_mfma_f32_16x16x32_bf16 v[8:11], v[136:139], v[208:211], v[8:11]
	v_mfma_f32_16x16x32_bf16 v[52:55], v[136:139], v[212:215], v[52:55]
	v_mfma_f32_16x16x32_bf16 v[60:63], v[140:143], v[216:219], v[60:63]
	v_mfma_f32_16x16x32_bf16 v[56:59], v[140:143], v[220:223], v[56:59]
	v_mfma_f32_16x16x32_bf16 v[48:51], v[140:143], v[224:227], v[48:51]
	v_mfma_f32_16x16x32_bf16 v[44:47], v[140:143], v[228:231], v[44:47]
	v_mfma_f32_16x16x32_bf16 v[40:43], v[144:147], v[216:219], v[40:43]
	v_mfma_f32_16x16x32_bf16 v[36:39], v[144:147], v[220:223], v[36:39]
	v_mfma_f32_16x16x32_bf16 v[20:23], v[144:147], v[224:227], v[20:23]
	v_mfma_f32_16x16x32_bf16 v[12:15], v[144:147], v[228:231], v[12:15]
	v_mfma_f32_16x16x32_bf16 v[16:19], v[148:151], v[216:219], v[16:19]
	v_mfma_f32_16x16x32_bf16 v[24:27], v[148:151], v[220:223], v[24:27]
	v_mfma_f32_16x16x32_bf16 v[28:31], v[148:151], v[224:227], v[28:31]
	v_mfma_f32_16x16x32_bf16 v[32:35], v[148:151], v[228:231], v[32:35]
	v_mfma_f32_16x16x32_bf16 v[0:3], v[152:155], v[216:219], v[0:3]
	v_mfma_f32_16x16x32_bf16 v[4:7], v[152:155], v[220:223], v[4:7]
	v_mfma_f32_16x16x32_bf16 v[8:11], v[152:155], v[224:227], v[8:11]
	v_mfma_f32_16x16x32_bf16 v[52:55], v[152:155], v[228:231], v[52:55]
	s_waitcnt vmcnt(0)
	ds_read_b128 v[124:127], v246
	ds_read_b128 v[128:131], v246 offset:2048
	ds_read_b128 v[132:135], v246 offset:4096
	ds_read_b128 v[136:139], v246 offset:6144
	ds_read_b128 v[200:203], v246 offset:8192
	ds_read_b128 v[204:207], v246 offset:10240
	ds_read_b128 v[208:211], v246 offset:12288
	ds_read_b128 v[212:215], v246 offset:14336
	ds_read_b128 v[140:143], v247
	ds_read_b128 v[144:147], v247 offset:2048
	ds_read_b128 v[148:151], v247 offset:4096
	ds_read_b128 v[152:155], v247 offset:6144
	ds_read_b128 v[216:219], v247 offset:8192
	ds_read_b128 v[220:223], v247 offset:10240
	ds_read_b128 v[224:227], v247 offset:12288
	ds_read_b128 v[228:231], v247 offset:14336
	s_waitcnt lgkmcnt(0)
	s_add_u32 m0, s54, 0x0
	s_nop 0
	global_load_lds_dwordx4 v232, s[50:51]
	s_add_u32 m0, s54, 0x400
	s_nop 0
	global_load_lds_dwordx4 v233, s[50:51]
	s_add_u32 m0, s54, 0x800
	s_nop 0
	global_load_lds_dwordx4 v234, s[50:51]
	s_add_u32 m0, s54, 0xc00
	s_nop 0
	global_load_lds_dwordx4 v235, s[50:51]
	s_add_u32 m0, s54, 0x1000
	s_nop 0
	global_load_lds_dwordx4 v236, s[50:51]
	s_add_u32 m0, s54, 0x1400
	s_nop 0
	global_load_lds_dwordx4 v237, s[50:51]
	s_add_u32 m0, s54, 0x1800
	s_nop 0
	global_load_lds_dwordx4 v238, s[50:51]
	s_add_u32 m0, s54, 0x1c00
	s_nop 0
	global_load_lds_dwordx4 v239, s[50:51]
	s_add_u32 m0, s54, 0x2000
	s_nop 0
	global_load_lds_dwordx4 v232, s[52:53]
	s_add_u32 m0, s54, 0x2400
	s_nop 0
	global_load_lds_dwordx4 v233, s[52:53]
	s_add_u32 m0, s54, 0x2800
	s_nop 0
	global_load_lds_dwordx4 v234, s[52:53]
	s_add_u32 m0, s54, 0x2c00
	s_nop 0
	global_load_lds_dwordx4 v235, s[52:53]
	s_add_u32 m0, s54, 0x3000
	s_nop 0
	global_load_lds_dwordx4 v236, s[52:53]
	s_add_u32 m0, s54, 0x3400
	s_nop 0
	global_load_lds_dwordx4 v237, s[52:53]
	s_add_u32 m0, s54, 0x3800
	s_nop 0
	global_load_lds_dwordx4 v238, s[52:53]
	s_add_u32 m0, s54, 0x3c00
	s_nop 0
	global_load_lds_dwordx4 v239, s[52:53]
	s_add_u32 s50, s50, 0x80
	s_addc_u32 s51, s51, 0
	s_add_u32 s52, s52, 0x80
	s_addc_u32 s53, s53, 0
	v_mfma_f32_16x16x32_bf16 v[60:63], v[124:127], v[200:203], v[60:63]
	v_mfma_f32_16x16x32_bf16 v[56:59], v[124:127], v[204:207], v[56:59]
; template <int NH>
; __device__ void gemm_sample_rows(const Params& p, const u16* __restrict__ A, const u16* __restrict__ Bt,
;                                  const float* __restrict__ resid, float* __restrict__ outf, unsigned char* smem, const int rep) {
;     ...
;     for (int ks = 0; ks < 8; ++ks) {
;       bf16x8 af[4], bfr[4];
; #pragma unroll
;       for (int mf = 0; mf < 4; ++mf) af[mf] = *(const bf16x8*)(ap + (size_t)(mf * 16) * K + ks * 32);
; #pragma unroll
;       for (int nf = 0; nf < 4; ++nf) bfr[nf] = *(const bf16x8*)(bp + (size_t)(nf * 16) * K + ks * 32);
; #pragma unroll
;       for (int mf = 0; mf < 4; ++mf)
; #pragma unroll
;         for (int nf = 0; nf < 4; ++nf)
;           acc[mf][nf] = __builtin_amdgcn_mfma_f32_16x16x32_bf16(af[mf], bfr[nf], acc[mf][nf], 0, 0, 0);
;     }
;     __syncthreads();
	v_mfma_f32_16x16x32_bf16 v[48:51], v[124:127], v[208:211], v[48:51]
	v_mfma_f32_16x16x32_bf16 v[44:47], v[124:127], v[212:215], v[44:47]
	v_mfma_f32_16x16x32_bf16 v[40:43], v[128:131], v[200:203], v[40:43]
	v_mfma_f32_16x16x32_bf16 v[36:39], v[128:131], v[204:207], v[36:39]
	v_mfma_f32_16x16x32_bf16 v[20:23], v[128:131], v[208:211], v[20:23]
	v_mfma_f32_16x16x32_bf16 v[12:15], v[128:131], v[212:215], v[12:15]
	v_mfma_f32_16x16x32_bf16 v[16:19], v[132:135], v[200:203], v[16:19]
	v_mfma_f32_16x16x32_bf16 v[24:27], v[132:135], v[204:207], v[24:27]
	v_mfma_f32_16x16x32_bf16 v[28:31], v[132:135], v[208:211], v[28:31]
	v_mfma_f32_16x16x32_bf16 v[32:35], v[132:135], v[212:215], v[32:35]
	v_mfma_f32_16x16x32_bf16 v[0:3], v[136:139], v[200:203], v[0:3]
	v_mfma_f32_16x16x32_bf16 v[4:7], v[136:139], v[204:207], v[4:7]
	v_mfma_f32_16x16x32_bf16 v[8:11], v[136:139], v[208:211], v[8:11]
	v_mfma_f32_16x16x32_bf16 v[52:55], v[136:139], v[212:215], v[52:55]
	v_mfma_f32_16x16x32_bf16 v[60:63], v[140:143], v[216:219], v[60:63]
	v_mfma_f32_16x16x32_bf16 v[56:59], v[140:143], v[220:223], v[56:59]
	v_mfma_f32_16x16x32_bf16 v[48:51], v[140:143], v[224:227], v[48:51]
	v_mfma_f32_16x16x32_bf16 v[44:47], v[140:143], v[228:231], v[44:47]
	v_mfma_f32_16x16x32_bf16 v[40:43], v[144:147], v[216:219], v[40:43]
	v_mfma_f32_16x16x32_bf16 v[36:39], v[144:147], v[220:223], v[36:39]
	v_mfma_f32_16x16x32_bf16 v[20:23], v[144:147], v[224:227], v[20:23]
	v_mfma_f32_16x16x32_bf16 v[12:15], v[144:147], v[228:231], v[12:15]
	v_mfma_f32_16x16x32_bf16 v[16:19], v[148:151], v[216:219], v[16:19]
	v_mfma_f32_16x16x32_bf16 v[24:27], v[148:151], v[220:223], v[24:27]
	v_mfma_f32_16x16x32_bf16 v[28:31], v[148:151], v[224:227], v[28:31]
	v_mfma_f32_16x16x32_bf16 v[32:35], v[148:151], v[228:231], v[32:35]
	v_mfma_f32_16x16x32_bf16 v[0:3], v[152:155], v[216:219], v[0:3]
	v_mfma_f32_16x16x32_bf16 v[4:7], v[152:155], v[220:223], v[4:7]
	v_mfma_f32_16x16x32_bf16 v[8:11], v[152:155], v[224:227], v[8:11]
	v_mfma_f32_16x16x32_bf16 v[52:55], v[152:155], v[228:231], v[52:55]
	s_waitcnt vmcnt(0)
	ds_read_b128 v[124:127], v246
	ds_read_b128 v[128:131], v246 offset:2048
	ds_read_b128 v[132:135], v246 offset:4096
	ds_read_b128 v[136:139], v246 offset:6144
	ds_read_b128 v[200:203], v246 offset:8192
	ds_read_b128 v[204:207], v246 offset:10240
	ds_read_b128 v[208:211], v246 offset:12288
	ds_read_b128 v[212:215], v246 offset:14336
	ds_read_b128 v[140:143], v247
	ds_read_b128 v[144:147], v247 offset:2048
	ds_read_b128 v[148:151], v247 offset:4096
	ds_read_b128 v[152:155], v247 offset:6144
	ds_read_b128 v[216:219], v247 offset:8192
	ds_read_b128 v[220:223], v247 offset:10240
	ds_read_b128 v[224:227], v247 offset:12288
	ds_read_b128 v[228:231], v247 offset:14336
	s_waitcnt lgkmcnt(0)
	v_mfma_f32_16x16x32_bf16 v[60:63], v[124:127], v[200:203], v[60:63]
	v_mfma_f32_16x16x32_bf16 v[56:59], v[124:127], v[204:207], v[56:59]
	v_mfma_f32_16x16x32_bf16 v[48:51], v[124:127], v[208:211], v[48:51]
	v_mfma_f32_16x16x32_bf16 v[44:47], v[124:127], v[212:215], v[44:47]
	v_mfma_f32_16x16x32_bf16 v[40:43], v[128:131], v[200:203], v[40:43]
	v_mfma_f32_16x16x32_bf16 v[36:39], v[128:131], v[204:207], v[36:39]
	v_mfma_f32_16x16x32_bf16 v[20:23], v[128:131], v[208:211], v[20:23]
	v_mfma_f32_16x16x32_bf16 v[12:15], v[128:131], v[212:215], v[12:15]
	v_mfma_f32_16x16x32_bf16 v[16:19], v[132:135], v[200:203], v[16:19]
	v_mfma_f32_16x16x32_bf16 v[24:27], v[132:135], v[204:207], v[24:27]
	v_mfma_f32_16x16x32_bf16 v[28:31], v[132:135], v[208:211], v[28:31]
	v_mfma_f32_16x16x32_bf16 v[32:35], v[132:135], v[212:215], v[32:35]
	v_mfma_f32_16x16x32_bf16 v[0:3], v[136:139], v[200:203], v[0:3]
	v_mfma_f32_16x16x32_bf16 v[4:7], v[136:139], v[204:207], v[4:7]
	v_mfma_f32_16x16x32_bf16 v[8:11], v[136:139], v[208:211], v[8:11]
	v_mfma_f32_16x16x32_bf16 v[52:55], v[136:139], v[212:215], v[52:55]
	v_mfma_f32_16x16x32_bf16 v[60:63], v[140:143], v[216:219], v[60:63]
	v_mfma_f32_16x16x32_bf16 v[56:59], v[140:143], v[220:223], v[56:59]
	v_mfma_f32_16x16x32_bf16 v[48:51], v[140:143], v[224:227], v[48:51]
	v_mfma_f32_16x16x32_bf16 v[44:47], v[140:143], v[228:231], v[44:47]
	v_mfma_f32_16x16x32_bf16 v[40:43], v[144:147], v[216:219], v[40:43]
	v_mfma_f32_16x16x32_bf16 v[36:39], v[144:147], v[220:223], v[36:39]
	v_mfma_f32_16x16x32_bf16 v[20:23], v[144:147], v[224:227], v[20:23]
	v_mfma_f32_16x16x32_bf16 v[12:15], v[144:147], v[228:231], v[12:15]
	v_mfma_f32_16x16x32_bf16 v[16:19], v[148:151], v[216:219], v[16:19]
	v_mfma_f32_16x16x32_bf16 v[24:27], v[148:151], v[220:223], v[24:27]
	v_mfma_f32_16x16x32_bf16 v[28:31], v[148:151], v[224:227], v[28:31]
	v_mfma_f32_16x16x32_bf16 v[32:35], v[148:151], v[228:231], v[32:35]
	v_mfma_f32_16x16x32_bf16 v[0:3], v[152:155], v[216:219], v[0:3]
	v_mfma_f32_16x16x32_bf16 v[4:7], v[152:155], v[220:223], v[4:7]
	v_mfma_f32_16x16x32_bf16 v[8:11], v[152:155], v[224:227], v[8:11]
	v_mfma_f32_16x16x32_bf16 v[52:55], v[152:155], v[228:231], v[52:55]
	s_movk_i32 s0, 0x200
	s_mov_b32 s1, 0
	s_cmpk_eq_i32 s0, 0x200
	s_waitcnt lgkmcnt(0)
	s_barrier
; template <int NH>
; __device__ void gemm_sample_rows(const Params& p, const u16* __restrict__ A, const u16* __restrict__ Bt,
;                                  const float* __restrict__ resid, float* __restrict__ outf, unsigned char* smem, const int rep) {
;     ...
;     __syncthreads();
;     {
;       const int h = (w * 256) / (K / NH);
; #pragma unroll
;       for (int mf = 0; mf < 4; ++mf)
; #pragma unroll
;         for (int r = 0; r < 4; ++r) {
;           const int row = mf * 16 + 4 * g + r;
;           const float sc = rstdS[row * NH + h];
; #pragma unroll
;           for (int nf = 0; nf < 4; ++nf) red[(w * 64 + row) * RS + nf * 16 + l15] = acc[mf][nf][r] * sc;
;         }
;     }
;     __syncthreads();
;     {
;       const int row = tid >> 3, c0 = (tid & 7) * 8;
;       float o[8];
;       const size_t gidx = (size_t)(m0 + row) * 1024 + n0 + c0;
	ds_read_b32 v68, v91
	s_lshl_b32 s0, s26, 6
	s_and_b32 s0, s0, 0x3c0
	s_add_i32 s26, s26, s96
	s_add_i32 s13, s13, s14
	s_waitcnt lgkmcnt(0)
	v_mul_f32_e32 v60, v60, v68
	v_mul_f32_e32 v56, v56, v68
	v_mul_f32_e32 v48, v48, v68
	v_mul_f32_e32 v44, v44, v68
	ds_write2_b32 v92, v60, v56 offset1:16
	ds_write2_b32 v92, v48, v44 offset0:32 offset1:48
	ds_read_b32 v44, v93
	s_add_i32 s15, s15, s16
	s_cmp_ge_i32 s26, s12
	s_waitcnt lgkmcnt(0)
	v_mul_f32_e32 v48, v61, v44
	v_mul_f32_e32 v56, v57, v44
	ds_write2_b32 v94, v48, v56 offset1:16
	v_mul_f32_e32 v48, v49, v44
	v_mul_f32_e32 v44, v45, v44
	ds_write2_b32 v94, v48, v44 offset0:32 offset1:48
	ds_read_b32 v44, v95
	s_waitcnt lgkmcnt(0)
	v_mul_f32_e32 v45, v62, v44
	v_mul_f32_e32 v48, v58, v44
	ds_write2_b32 v96, v45, v48 offset1:16
	v_mul_f32_e32 v45, v50, v44
	v_mul_f32_e32 v44, v46, v44
	ds_write2_b32 v96, v45, v44 offset0:32 offset1:48
	ds_read_b32 v44, v97
	s_waitcnt lgkmcnt(0)
	v_mul_f32_e32 v45, v63, v44
	v_mul_f32_e32 v46, v59, v44
	ds_write2_b32 v98, v45, v46 offset1:16
	v_mul_f32_e32 v45, v51, v44
	v_mul_f32_e32 v44, v47, v44
	ds_write2_b32 v98, v45, v44 offset0:32 offset1:48
	ds_read_b32 v44, v99
	s_waitcnt lgkmcnt(0)
	v_mul_f32_e32 v40, v40, v44
	v_mul_f32_e32 v36, v36, v44
	v_mul_f32_e32 v20, v20, v44
	v_mul_f32_e32 v12, v12, v44
	ds_write2_b32 v100, v40, v36 offset1:16
	ds_write2_b32 v100, v20, v12 offset0:32 offset1:48
	ds_read_b32 v12, v101
	v_add_u32_e32 v40, 0xc318, v65
	s_waitcnt lgkmcnt(0)
	v_mul_f32_e32 v20, v41, v12
	v_mul_f32_e32 v36, v37, v12
	ds_write2_b32 v102, v20, v36 offset1:16
	v_mul_f32_e32 v20, v21, v12
	v_mul_f32_e32 v12, v13, v12
	ds_write2_b32 v102, v20, v12 offset0:32 offset1:48
	ds_read_b32 v12, v103
	v_add_u32_e32 v36, 0x4118, v65
	s_waitcnt lgkmcnt(0)
	v_mul_f32_e32 v13, v42, v12
	v_mul_f32_e32 v20, v38, v12
	ds_write2_b32 v104, v13, v20 offset1:16
	v_mul_f32_e32 v13, v22, v12
	v_mul_f32_e32 v12, v14, v12
	ds_write2_b32 v104, v13, v12 offset0:32 offset1:48
	ds_read_b32 v12, v105
	v_add_u32_e32 v20, 0xc308, v65
	v_add_u32_e32 v22, 0x4110, v65
	v_add_u32_e32 v38, 0x8218, v65
	s_waitcnt lgkmcnt(0)
	v_mul_f32_e32 v13, v43, v12
	v_mul_f32_e32 v14, v39, v12
	ds_write2_b32 v106, v13, v14 offset1:16
	v_mul_f32_e32 v13, v23, v12
	v_mul_f32_e32 v12, v15, v12
	ds_write2_b32 v106, v13, v12 offset0:32 offset1:48
	ds_read_b32 v12, v107
	s_waitcnt lgkmcnt(0)
	v_mul_f32_e32 v13, v16, v12
	v_mul_f32_e32 v14, v24, v12
	ds_write2_b32 v108, v13, v14 offset1:16
	v_mul_f32_e32 v13, v28, v12
	v_mul_f32_e32 v12, v32, v12
	ds_write2_b32 v108, v13, v12 offset0:32 offset1:48
	ds_read_b32 v12, v109
	v_add_u32_e32 v16, 0x4108, v65
	v_add_u32_e32 v24, 0x8210, v65
	s_waitcnt lgkmcnt(0)
	v_mul_f32_e32 v13, v17, v12
	v_mul_f32_e32 v14, v25, v12
	ds_write2_b32 v110, v13, v14 offset1:16
	v_mul_f32_e32 v13, v29, v12
	v_mul_f32_e32 v12, v33, v12
	ds_write2_b32 v110, v13, v12 offset0:32 offset1:48
	ds_read_b32 v12, v111
	s_waitcnt lgkmcnt(0)
	v_mul_f32_e32 v13, v18, v12
	v_mul_f32_e32 v14, v26, v12
	ds_write2_b32 v112, v13, v14 offset1:16
	v_mul_f32_e32 v13, v30, v12
	v_mul_f32_e32 v12, v34, v12
	ds_write2_b32 v112, v13, v12 offset0:32 offset1:48
	ds_read_b32 v12, v113
	v_add_u32_e32 v18, 0x8208, v65
	v_add_u32_e32 v34, 0xc310, v65
	s_waitcnt lgkmcnt(0)
	v_mul_f32_e32 v13, v19, v12
	v_mul_f32_e32 v14, v27, v12
	ds_write2_b32 v114, v13, v14 offset1:16
	v_mul_f32_e32 v13, v31, v12
	v_mul_f32_e32 v12, v35, v12
	ds_write2_b32 v114, v13, v12 offset0:32 offset1:48
	ds_read_b32 v12, v115
	v_add_u32_e32 v14, 0xc300, v65
	s_waitcnt lgkmcnt(0)
	v_mul_f32_e32 v0, v0, v12
	v_mul_f32_e32 v4, v4, v12
	ds_write2_b32 v116, v0, v4 offset1:16
	v_mul_f32_e32 v0, v8, v12
	v_mul_f32_e32 v4, v52, v12
	ds_write2_b32 v116, v0, v4 offset0:32 offset1:48
	ds_read_b32 v0, v117
	v_add_u32_e32 v12, 0x8200, v65
	s_waitcnt lgkmcnt(0)
	v_mul_f32_e32 v1, v1, v0
	v_mul_f32_e32 v4, v5, v0
	ds_write2_b32 v118, v1, v4 offset1:16
	v_mul_f32_e32 v1, v9, v0
	v_mul_f32_e32 v0, v53, v0
	ds_write2_b32 v118, v1, v0 offset0:32 offset1:48
	ds_read_b32 v0, v119
	s_waitcnt lgkmcnt(0)
	v_mul_f32_e32 v1, v2, v0
	v_mul_f32_e32 v2, v6, v0
	ds_write2_b32 v120, v1, v2 offset1:16
	v_mul_f32_e32 v1, v10, v0
	v_mul_f32_e32 v0, v54, v0
	ds_write2_b32 v120, v1, v0 offset0:32 offset1:48
	ds_read_b32 v0, v121
	s_waitcnt lgkmcnt(0)
	v_mul_f32_e32 v1, v3, v0
	v_mul_f32_e32 v2, v7, v0
	ds_write2_b32 v122, v1, v2 offset1:16
	v_mul_f32_e32 v1, v11, v0
	v_mul_f32_e32 v0, v55, v0
	ds_write2_b32 v122, v1, v0 offset0:32 offset1:48
	v_add_u32_e32 v0, s27, v197
	v_ashrrev_i32_e32 v1, 31, v0
	v_lshlrev_b64 v[0:1], 10, v[0:1]
	v_or_b32_e32 v0, s0, v0
	v_or_b32_e32 v0, v0, v64
	v_lshlrev_b64 v[8:9], 2, v[0:1]
	v_lshl_add_u64 v[10:11], s[6:7], 0, v[8:9]
	s_waitcnt lgkmcnt(0)
	s_barrier
; template <int NH>
; __device__ void gemm_sample_rows(const Params& p, const u16* __restrict__ A, const u16* __restrict__ Bt,
;                                  const float* __restrict__ resid, float* __restrict__ outf, unsigned char* smem, const int rep) {
;     ...
;     {
;       const int row = tid >> 3, c0 = (tid & 7) * 8;
;       float o[8];
;       const size_t gidx = (size_t)(m0 + row) * 1024 + n0 + c0;
;       const float* rp = resid ? resid + gidx : p.x_sample + (size_t)(m0 - NPROMPT + row) * 1024 + n0 + c0;
;       const float4 r0 = *(const float4*)rp, r1 = *(const float4*)(rp + 4);
;       o[0] = r0.x; o[1] = r0.y; o[2] = r0.z; o[3] = r0.w; o[4] = r1.x; o[5] = r1.y; o[6] = r1.z; o[7] = r1.w;
; #pragma unroll
;       for (int ww = 0; ww < 8; ++ww)
; #pragma unroll
;         for (int j = 0; j < 8; ++j) o[j] += red[(ww * 64 + row) * RS + c0 + j];
;       *(float4*)(outf + gidx) = make_float4(o[0], o[1], o[2], o[3]);
;       *(float4*)(outf + gidx + 4) = make_float4(o[4], o[5], o[6], o[7]);
;     }
;     __syncthreads();
	global_load_dwordx4 v[0:3], v[10:11], off
	global_load_dwordx4 v[4:7], v[10:11], off offset:16
	v_add_u32_e32 v10, 0x4100, v65
	ds_read2_b32 v[10:11], v10 offset1:1
	ds_read2_b32 v[12:13], v12 offset1:1
	ds_read2_b32 v[14:15], v14 offset1:1
	ds_read2_b32 v[16:17], v16 offset1:1
	ds_read2_b32 v[18:19], v18 offset1:1
	ds_read2_b32 v[20:21], v20 offset1:1
	ds_read2_b32 v[22:23], v22 offset1:1
	ds_read2_b32 v[24:25], v24 offset1:1
	ds_read2_b32 v[26:27], v65 offset1:1
	ds_read2_b32 v[28:29], v65 offset0:2 offset1:3
	ds_read2_b32 v[30:31], v65 offset0:4 offset1:5
	ds_read2_b32 v[32:33], v65 offset0:6 offset1:7
	ds_read2_b32 v[34:35], v34 offset1:1
	ds_read2_b32 v[36:37], v36 offset1:1
	ds_read2_b32 v[38:39], v38 offset1:1
	ds_read2_b32 v[40:41], v40 offset1:1
	ds_read2_b32 v[42:43], v72 offset1:1
	ds_read2_b32 v[44:45], v73 offset1:1
	ds_read2_b32 v[46:47], v74 offset1:1
	ds_read2_b32 v[48:49], v75 offset1:1
	ds_read2_b32 v[50:51], v76 offset1:1
	ds_read2_b32 v[52:53], v77 offset1:1
	ds_read2_b32 v[54:55], v78 offset1:1
	ds_read2_b32 v[56:57], v79 offset1:1
	ds_read2_b32 v[58:59], v80 offset1:1
	ds_read2_b32 v[60:61], v81 offset1:1
	ds_read2_b32 v[62:63], v82 offset1:1
	ds_read2_b32 v[68:69], v83 offset1:1
	ds_read2_b32 v[70:71], v84 offset1:1
	ds_read2_b32 v[124:125], v85 offset1:1
	ds_read2_b32 v[126:127], v86 offset1:1
	ds_read2_b32 v[128:129], v87 offset1:1
	v_lshl_add_u64 v[8:9], s[8:9], 0, v[8:9]
	s_waitcnt vmcnt(1) lgkmcnt(14)
	v_pk_add_f32 v[0:1], v[0:1], v[26:27]
	v_pk_add_f32 v[2:3], v[2:3], v[28:29]
	v_pk_add_f32 v[0:1], v[0:1], v[10:11]
	v_pk_add_f32 v[2:3], v[2:3], v[16:17]
	v_pk_add_f32 v[0:1], v[0:1], v[12:13]
	v_pk_add_f32 v[2:3], v[2:3], v[18:19]
	v_pk_add_f32 v[0:1], v[0:1], v[14:15]
	v_pk_add_f32 v[2:3], v[2:3], v[20:21]
	v_pk_add_f32 v[0:1], v[0:1], v[42:43]
	v_pk_add_f32 v[2:3], v[2:3], v[44:45]
	s_waitcnt lgkmcnt(11)
	v_pk_add_f32 v[0:1], v[0:1], v[50:51]
	s_waitcnt lgkmcnt(10)
	v_pk_add_f32 v[2:3], v[2:3], v[52:53]
	s_waitcnt lgkmcnt(7)
	v_pk_add_f32 v[0:1], v[0:1], v[58:59]
	s_waitcnt lgkmcnt(6)
	v_pk_add_f32 v[2:3], v[2:3], v[60:61]
	s_waitcnt vmcnt(0)
	v_pk_add_f32 v[4:5], v[4:5], v[30:31]
	v_pk_add_f32 v[6:7], v[6:7], v[32:33]
	s_waitcnt lgkmcnt(3)
	v_pk_add_f32 v[0:1], v[0:1], v[70:71]
	s_waitcnt lgkmcnt(2)
	v_pk_add_f32 v[2:3], v[2:3], v[124:125]
	v_pk_add_f32 v[4:5], v[4:5], v[22:23]
	global_store_dwordx4 v[8:9], v[0:3], off
	v_pk_add_f32 v[4:5], v[4:5], v[24:25]
	s_nop 0
	v_pk_add_f32 v[0:1], v[6:7], v[36:37]
	v_pk_add_f32 v[4:5], v[4:5], v[34:35]
	v_pk_add_f32 v[0:1], v[0:1], v[38:39]
	v_pk_add_f32 v[4:5], v[4:5], v[46:47]
	v_pk_add_f32 v[0:1], v[0:1], v[40:41]
	v_pk_add_f32 v[4:5], v[4:5], v[54:55]
	v_pk_add_f32 v[0:1], v[0:1], v[48:49]
	v_pk_add_f32 v[4:5], v[4:5], v[62:63]
	v_pk_add_f32 v[0:1], v[0:1], v[56:57]
	s_waitcnt lgkmcnt(1)
	v_pk_add_f32 v[4:5], v[4:5], v[126:127]
	v_pk_add_f32 v[0:1], v[0:1], v[68:69]
	s_waitcnt lgkmcnt(0)
	v_pk_add_f32 v[6:7], v[0:1], v[128:129]
	global_store_dwordx4 v[8:9], v[4:7], off offset:16
	s_barrier
	s_cbranch_scc0 .LBB0_2031
